# hgA_unit: next unit's V/z/lb loads prefetched mid-unit (SGPR base + per-thread offsets), top-of-unit vmcnt(0) removed
# baseline (speedup 1.0000x reference)
.LBB0_307:
	v_readlane_b32 s0, v253, 56
	v_readlane_b32 s1, v253, 57
	s_andn2_b64 vcc, exec, s[0:1]
	s_cbranch_vccnz .LBB0_318
	s_lshl_b32 s6, s16, 5
	v_readlane_b32 s7, v254, 60
	s_mov_b32 s12, s62
	v_lshrrev_b32_e32 v123, 2, v200
	v_mul_u32_u24_e32 v123, 0x1f00, v123
	v_and_b32_e32 v124, 3, v200
	v_lshl_add_u32 v123, v124, 5, v123
	v_add_u32_e32 v123, 0x1b00, v123
	v_and_b32_e32 v124, 63, v200
	v_lshrrev_b32_e32 v125, 7, v200
	v_mul_u32_u24_e32 v125, 0x3e000, v125
	v_lshl_add_u32 v125, v124, 1, v125
	v_bfe_u32 v126, v200, 6, 1
	v_lshl_add_u32 v125, v126, 9, v125
	v_add_u32_e32 v125, 0x1700, v125
	v_lshlrev_b32_e32 v124, 2, v124
	v_add_u32_e32 v140, 0xf80, v125
	v_add_u32_e32 v141, 0x4d80, v125
	v_add_u32_e32 v142, 0x8b80, v125
	v_add_u32_e32 v143, 0xc980, v125
	v_add_u32_e32 v144, 0x10780, v125
	v_add_u32_e32 v145, 0x14580, v125
	v_add_u32_e32 v146, 0x18380, v125
	v_add_u32_e32 v147, 0x1c180, v125
	v_add_u32_e32 v148, 0x1ff80, v125
	v_add_u32_e32 v149, 0x23d80, v125
	v_add_u32_e32 v150, 0x27b80, v125
	v_add_u32_e32 v151, 0x2b980, v125
	v_add_u32_e32 v152, 0x2f780, v125
	v_add_u32_e32 v153, 0x33580, v125
	v_add_u32_e32 v154, 0x37380, v125
	v_add_u32_e32 v155, 0x3b180, v125
	s_mov_b32 s100, s12
	s_bfe_u32 m0, s100, 0x20005
	s_lshr_b32 s101, s100, 7
	s_lshl_b32 s101, s101, 12
	s_and_b32 s100, s100, 31
	s_lshl_b32 s100, s100, 7
	s_or_b32 s101, s101, s100
	s_mul_i32 s101, s101, 0x1f00
	s_lshl_b32 s100, m0, 7
	s_add_u32 s101, s101, s100
	s_add_u32 s100, s22, s101
	s_addc_u32 s101, s23, 0
	v_readlane_b32 vcc_lo, v255, 33
	s_lshl_b32 m0, m0, 6
	s_nop 1
	s_or_b32 m0, m0, vcc_lo
	s_lshl_b32 m0, m0, 2
	v_readlane_b32 vcc_lo, v253, 10
	v_readlane_b32 vcc_hi, v253, 11
	s_nop 1
	s_add_u32 vcc_lo, vcc_lo, m0
	s_addc_u32 vcc_hi, vcc_hi, 0
	global_load_dwordx4 v[114:117], v123, s[100:101]
	global_load_dwordx4 v[118:121], v123, s[100:101] offset:16
	global_load_dword v122, v124, vcc
	global_load_ushort v80, v140, s[100:101] offset:-3968
	global_load_ushort v81, v140, s[100:101] offset:3968
	global_load_ushort v82, v141, s[100:101] offset:-3968
	global_load_ushort v83, v141, s[100:101] offset:3968
	global_load_ushort v84, v142, s[100:101] offset:-3968
	global_load_ushort v85, v142, s[100:101] offset:3968
	global_load_ushort v86, v143, s[100:101] offset:-3968
	global_load_ushort v87, v143, s[100:101] offset:3968
	global_load_ushort v88, v144, s[100:101] offset:-3968
	global_load_ushort v89, v144, s[100:101] offset:3968
	global_load_ushort v90, v145, s[100:101] offset:-3968
	global_load_ushort v91, v145, s[100:101] offset:3968
	global_load_ushort v92, v146, s[100:101] offset:-3968
	global_load_ushort v93, v146, s[100:101] offset:3968
	global_load_ushort v94, v147, s[100:101] offset:-3968
	global_load_ushort v95, v147, s[100:101] offset:3968
	global_load_ushort v96, v148, s[100:101] offset:-3968
	global_load_ushort v97, v148, s[100:101] offset:3968
	global_load_ushort v98, v149, s[100:101] offset:-3968
	global_load_ushort v99, v149, s[100:101] offset:3968
	global_load_ushort v100, v150, s[100:101] offset:-3968
	global_load_ushort v101, v150, s[100:101] offset:3968
	global_load_ushort v102, v151, s[100:101] offset:-3968
	global_load_ushort v103, v151, s[100:101] offset:3968
	global_load_ushort v104, v152, s[100:101] offset:-3968
	global_load_ushort v105, v152, s[100:101] offset:3968
	global_load_ushort v106, v153, s[100:101] offset:-3968
	global_load_ushort v107, v153, s[100:101] offset:3968
	global_load_ushort v108, v154, s[100:101] offset:-3968
	global_load_ushort v109, v154, s[100:101] offset:3968
	global_load_ushort v110, v155, s[100:101] offset:-3968
	global_load_ushort v111, v155, s[100:101] offset:3968
	s_waitcnt vmcnt(0)
	s_branch .LBB0_310

.LBB0_310:
	s_and_b32 s13, s12, 31
	v_mov_b32_e32 v4, v200
	s_and_b32 s0, s7, 0xfffff000
	s_lshl_b32 s1, s13, 7
	s_or_b32 s0, s0, s1
	v_ashrrev_i32_e32 v0, 2, v4
	s_ashr_i32 s1, s0, 31
	v_ashrrev_i32_e32 v1, 31, v0
	v_lshl_add_u64 v[2:3], s[0:1], 0, v[0:1]
	v_mov_b64_e32 v[12:13], s[22:23]
	s_ashr_i32 s14, s12, 5
	v_mad_u64_u32 v[8:9], s[2:3], v2, s93, v[12:13]
	s_lshl_b32 s2, s14, 6
	s_and_b32 s2, s2, 0xc0
	v_mad_i32_i24 v9, v3, s93, v9
	s_lshl_b32 s96, s2, 1
	v_lshlrev_b32_e32 v1, 5, v4
	v_lshl_add_u64 v[2:3], v[8:9], 0, s[96:97]
	v_and_b32_e32 v128, 0x60, v1
	v_lshl_add_u64 v[2:3], v[2:3], 0, v[128:129]
	s_mov_b64 s[20:21], 0x1b00
	v_lshl_add_u64 v[14:15], v[2:3], 0, s[20:21]
	v_add_co_u32_e32 v2, vcc, s86, v2
	s_movk_i32 s3, 0x90
	s_nop 0
	v_addc_co_u32_e32 v3, vcc, 0, v3, vcc
	v_mul_lo_u32 v0, v0, s3
	v_ashrrev_i32_e32 v15, 7, v4
	v_add3_u32 v7, 16, v0, v128
	v_lshlrev_b32_e32 v0, 5, v15
	v_ashrrev_i32_e32 v1, 31, v0
	v_ashrrev_i32_e32 v6, 6, v4
	v_lshl_add_u64 v[0:1], v[0:1], 0, s[0:1]
	v_and_b32_e32 v22, 1, v6
	v_mad_u64_u32 v[2:3], s[0:1], v0, s93, v[12:13]
	v_mad_i32_i24 v3, v1, s93, v3
	v_cmp_eq_u32_e32 vcc, 0, v22
	v_mov_b32_e32 v0, 0x1900
	v_mov_b32_e32 v1, 0x1700
	v_cndmask_b32_e32 v128, v0, v1, vcc
	v_and_b32_e32 v5, 63, v4
	v_lshl_add_u64 v[0:1], v[2:3], 0, v[128:129]
	v_lshl_add_u64 v[0:1], v[0:1], 0, s[96:97]
	v_lshlrev_b32_e32 v128, 1, v5
	v_lshl_add_u64 v[0:1], v[0:1], 0, v[128:129]
	v_add_co_u32_e32 v2, vcc, s86, v0
	s_nop 0
	v_addc_co_u32_e32 v3, vcc, 0, v1, vcc
	s_movk_i32 s0, 0x3000
	v_add_co_u32_e32 v12, vcc, s0, v0
	v_readlane_b32 s0, v255, 33
	s_nop 0
	v_addc_co_u32_e32 v13, vcc, 0, v1, vcc
	s_nop 0
	v_readlane_b32 s1, v255, 34
	s_or_b32 s0, s2, s0
	v_or_b32_e32 v2, s0, v5
	v_readlane_b32 s0, v253, 10
	v_ashrrev_i32_e32 v3, 31, v2
	v_readlane_b32 s1, v253, 11
	v_lshl_add_u32 v75, v22, 10, 16
	s_movk_i32 s2, 0x4400
	v_lshl_add_u64 v[2:3], v[2:3], 2, s[0:1]
	s_movk_i32 s0, 0x5000
	v_add_co_u32_e32 v2, vcc, s0, v0
	s_movk_i32 s0, 0x7000
	s_nop 0
	v_addc_co_u32_e32 v3, vcc, 0, v1, vcc
	v_add_co_u32_e32 v2, vcc, s0, v0
	s_mov_b32 s0, 0x9000
	s_nop 0
	v_addc_co_u32_e32 v3, vcc, 0, v1, vcc
	v_add_co_u32_e32 v2, vcc, s0, v0
	s_mov_b32 s0, 0xb000
	s_nop 0
	v_addc_co_u32_e32 v3, vcc, 0, v1, vcc
	v_add_co_u32_e64 v2, s[0:1], s0, v0
	v_cmp_eq_u32_e32 vcc, 1, v22
	s_nop 0
	v_addc_co_u32_e64 v3, s[0:1], 0, v1, s[0:1]
	s_waitcnt vmcnt(48)
	ds_write_b128 v7, v[114:117] offset:36864
	ds_write_b128 v7, v[118:121] offset:36880
	v_mov_b32_e32 v16, v122
	s_mov_b32 s0, 0xd000
	v_mad_u32_u24 v22, v22, s2, v75
	s_movk_i32 s2, 0x1200
	v_readfirstlane_b32 s15, v6
	v_cmp_gt_i32_e64 s[42:43], 0, v15
	v_cmp_gt_i32_e64 s[40:41], 1, v15
	v_cmp_gt_i32_e64 s[44:45], 2, v15
	s_waitcnt vmcnt(47)
	v_lshlrev_b32_e32 v2, 16, v80
	v_max_f32_e32 v2, v2, v2
	v_med3_f32 v2, v2, s85, v215
	v_mul_f32_e32 v2, 0xbfb8aa3b, v2
	v_exp_f32_e32 v7, v2
	s_waitcnt vmcnt(46)
	v_lshlrev_b32_e32 v3, 16, v81
	v_max_f32_e32 v3, v3, v3
	v_med3_f32 v3, v3, s85, v215
	v_mul_f32_e32 v2, 0xbfb8aa3b, v3
	s_waitcnt vmcnt(45)
	v_lshlrev_b32_e32 v9, 16, v82
	v_exp_f32_e32 v8, v2
	v_max_f32_e32 v2, v9, v9
	v_med3_f32 v2, v2, s85, v215
	v_add_f32_e32 v3, 1.0, v7
	v_mul_f32_e32 v2, 0xbfb8aa3b, v2
	v_rcp_f32_e32 v9, v3
	v_add_f32_e32 v3, 1.0, v8
	v_exp_f32_e32 v14, v2
	v_add_co_u32_e64 v2, s[0:1], s0, v0
	v_rcp_f32_e32 v10, v3
	s_nop 0
	v_addc_co_u32_e64 v3, s[0:1], 0, v1, s[0:1]
	v_add_f32_e32 v2, 1.0, v14
	s_mov_b32 s0, 0xf000
	v_rcp_f32_e32 v17, v2
	v_add_co_u32_e64 v2, s[0:1], s0, v0
	v_sub_f32_e32 v11, 1.0, v16
	v_addc_co_u32_e64 v3, s[0:1], 0, v1, s[0:1]
	s_waitcnt vmcnt(44)
	v_lshlrev_b32_e32 v2, 16, v83
	v_max_f32_e32 v2, v2, v2
	v_med3_f32 v2, v2, s85, v215
	v_mul_f32_e32 v2, 0xbfb8aa3b, v2
	v_exp_f32_e32 v18, v2
	s_mov_b32 s0, 0x11000
	v_add_co_u32_e64 v2, s[0:1], s0, v0
	v_fma_f32 v13, v11, v17, v16
	s_nop 0
	v_addc_co_u32_e64 v3, s[0:1], 0, v1, s[0:1]
	v_mul_f32_e32 v2, v11, v14
	v_mul_f32_e32 v14, v2, v17
	v_add_f32_e32 v2, 1.0, v18
	s_mov_b32 s0, 0x13000
	v_rcp_f32_e32 v19, v2
	v_add_co_u32_e64 v2, s[0:1], s0, v0
	v_fma_f32 v31, v11, v9, v16
	s_nop 0
	v_addc_co_u32_e64 v3, s[0:1], 0, v1, s[0:1]
	s_waitcnt vmcnt(43)
	v_lshlrev_b32_e32 v2, 16, v84
	v_max_f32_e32 v2, v2, v2
	v_med3_f32 v2, v2, s85, v215
	v_mul_f32_e32 v2, 0xbfb8aa3b, v2
	v_exp_f32_e32 v20, v2
	v_mul_f32_e32 v2, v11, v18
	v_mul_f32_e32 v18, v2, v19
	s_mov_b32 s0, 0x15000
	v_add_f32_e32 v2, 1.0, v20
	v_rcp_f32_e32 v21, v2
	s_waitcnt vmcnt(42)
	v_lshlrev_b32_e32 v2, 16, v85
	v_max_f32_e32 v2, v2, v2
	v_med3_f32 v2, v2, s85, v215
	v_mul_f32_e32 v2, 0xbfb8aa3b, v2
	v_exp_f32_e32 v23, v2
	v_add_co_u32_e64 v2, s[0:1], s0, v0
	v_fma_f32 v17, v11, v19, v16
	s_nop 0
	v_addc_co_u32_e64 v3, s[0:1], 0, v1, s[0:1]
	v_add_f32_e32 v3, 1.0, v23
	v_rcp_f32_e32 v30, v3
	s_waitcnt vmcnt(41)
	v_lshlrev_b32_e32 v3, 16, v86
	v_max_f32_e32 v3, v3, v3
	v_med3_f32 v3, v3, s85, v215
	v_mul_f32_e32 v3, 0xbfb8aa3b, v3
	v_exp_f32_e32 v33, v3
	v_mul_f32_e32 v2, v11, v20
	v_fma_f32 v19, v11, v21, v16
	v_mul_f32_e32 v21, v2, v21
	v_add_f32_e32 v2, 1.0, v33
	s_mov_b32 s0, 0x17000
	v_rcp_f32_e32 v34, v2
	v_add_co_u32_e64 v2, s[0:1], s0, v0
	v_mul_f32_e32 v23, v11, v23
	s_nop 0
	v_addc_co_u32_e64 v3, s[0:1], 0, v1, s[0:1]
	s_mov_b32 s0, 0x19000
	v_add_co_u32_e64 v2, s[0:1], s0, v0
	v_fma_f32 v20, v11, v30, v16
	s_nop 0
	v_addc_co_u32_e64 v3, s[0:1], 0, v1, s[0:1]
	s_mov_b32 s0, 0x1b000
	s_nop 0
	v_add_co_u32_e64 v24, s[0:1], s0, v0
	v_fma_f32 v12, v11, v10, v16
	s_nop 0
	v_addc_co_u32_e64 v25, s[0:1], 0, v1, s[0:1]
	s_waitcnt vmcnt(40)
	v_lshlrev_b32_e32 v2, 16, v87
	v_max_f32_e32 v2, v2, v2
	v_med3_f32 v2, v2, s85, v215
	v_mul_f32_e32 v2, 0xbfb8aa3b, v2
	v_exp_f32_e32 v2, v2
	v_mul_f32_e32 v24, v23, v30
	v_mul_f32_e32 v3, v11, v33
	v_mul_f32_e32 v26, v3, v34
	v_add_f32_e32 v25, 1.0, v2
	v_rcp_f32_e32 v30, v25
	s_waitcnt vmcnt(39)
	v_lshlrev_b32_e32 v25, 16, v88
	v_max_f32_e32 v25, v25, v25
	v_med3_f32 v25, v25, s85, v215
	v_mul_f32_e32 v25, 0xbfb8aa3b, v25
	v_exp_f32_e32 v33, v25
	v_fma_f32 v23, v11, v34, v16
	v_mul_f32_e32 v2, v11, v2
	v_fma_f32 v25, v11, v30, v16
	v_add_f32_e32 v3, 1.0, v33
	v_rcp_f32_e32 v34, v3
	s_waitcnt vmcnt(38)
	v_lshlrev_b32_e32 v3, 16, v89
	v_max_f32_e32 v3, v3, v3
	v_med3_f32 v3, v3, s85, v215
	v_mul_f32_e32 v3, 0xbfb8aa3b, v3
	v_exp_f32_e32 v37, v3
	v_mul_f32_e32 v28, v2, v30
	v_mul_f32_e32 v30, v11, v33
	s_mov_b32 s0, 0x1d000
	v_add_f32_e32 v2, 1.0, v37
	v_rcp_f32_e32 v33, v2
	s_waitcnt vmcnt(37)
	v_lshlrev_b32_e32 v2, 16, v90
	v_max_f32_e32 v2, v2, v2
	v_med3_f32 v2, v2, s85, v215
	v_mul_f32_e32 v2, 0xbfb8aa3b, v2
	v_exp_f32_e32 v39, v2
	v_add_co_u32_e64 v2, s[0:1], s0, v0
	v_fma_f32 v27, v11, v34, v16
	s_nop 0
	v_addc_co_u32_e64 v3, s[0:1], 0, v1, s[0:1]
	v_add_f32_e32 v2, 1.0, v39
	s_mov_b32 s0, 0x1f000
	v_mul_f32_e32 v30, v30, v34
	v_mul_f32_e32 v34, v11, v37
	v_rcp_f32_e32 v37, v2
	v_add_co_u32_e64 v2, s[0:1], s0, v0
	v_fma_f32 v29, v11, v33, v16
	s_nop 0
	v_addc_co_u32_e64 v3, s[0:1], 0, v1, s[0:1]
	s_waitcnt vmcnt(36)
	v_lshlrev_b32_e32 v2, 16, v91
	v_max_f32_e32 v2, v2, v2
	v_med3_f32 v2, v2, s85, v215
	v_mul_f32_e32 v2, 0xbfb8aa3b, v2
	s_mov_b32 s0, 0x20000
	v_exp_f32_e32 v40, v2
	v_add_co_u32_e64 v2, s[0:1], s0, v0
	v_mul_f32_e32 v33, v34, v33
	s_nop 0
	v_addc_co_u32_e64 v3, s[0:1], 0, v1, s[0:1]
	v_add_f32_e32 v2, 1.0, v40
	s_mov_b32 s0, 0x22000
	v_mul_f32_e32 v34, v11, v39
	v_rcp_f32_e32 v39, v2
	v_add_co_u32_e64 v2, s[0:1], s0, v0
	v_fma_f32 v32, v11, v37, v16
	s_nop 0
	v_addc_co_u32_e64 v3, s[0:1], 0, v1, s[0:1]
	s_waitcnt vmcnt(35)
	v_lshlrev_b32_e32 v2, 16, v92
	v_max_f32_e32 v2, v2, v2
	v_med3_f32 v2, v2, s85, v215
	v_mul_f32_e32 v2, 0xbfb8aa3b, v2
	v_exp_f32_e32 v41, v2
	s_mov_b32 s0, 0x24000
	v_mul_f32_e32 v35, v34, v37
	v_mul_f32_e32 v37, v11, v40
	v_add_f32_e32 v2, 1.0, v41
	v_rcp_f32_e32 v40, v2
	v_add_co_u32_e64 v2, s[0:1], s0, v0
	v_fma_f32 v34, v11, v39, v16
	s_nop 0
	v_addc_co_u32_e64 v3, s[0:1], 0, v1, s[0:1]
	s_waitcnt vmcnt(34)
	v_lshlrev_b32_e32 v2, 16, v93
	v_max_f32_e32 v2, v2, v2
	v_med3_f32 v2, v2, s85, v215
	v_mul_f32_e32 v2, 0xbfb8aa3b, v2
	v_exp_f32_e32 v45, v2
	s_mov_b32 s0, 0x26000
	v_mul_f32_e32 v37, v37, v39
	v_mul_f32_e32 v39, v11, v41
	v_add_f32_e32 v2, 1.0, v45
	v_rcp_f32_e32 v47, v2
	s_waitcnt vmcnt(33)
	v_lshlrev_b32_e32 v2, 16, v94
	v_max_f32_e32 v2, v2, v2
	v_med3_f32 v2, v2, s85, v215
	v_mul_f32_e32 v2, 0xbfb8aa3b, v2
	v_exp_f32_e32 v49, v2
	v_add_co_u32_e64 v2, s[0:1], s0, v0
	v_fma_f32 v36, v11, v40, v16
	s_nop 0
	v_addc_co_u32_e64 v3, s[0:1], 0, v1, s[0:1]
	v_add_f32_e32 v2, 1.0, v49
	s_mov_b32 s0, 0x28000
	v_rcp_f32_e32 v51, v2
	v_add_co_u32_e64 v2, s[0:1], s0, v0
	v_mul_f32_e32 v39, v39, v40
	s_nop 0
	v_addc_co_u32_e64 v3, s[0:1], 0, v1, s[0:1]
	s_mov_b32 s0, 0x2a000
	s_nop 0
	v_add_co_u32_e64 v40, s[0:1], s0, v0
	v_fma_f32 v38, v11, v47, v16
	s_nop 0
	v_addc_co_u32_e64 v41, s[0:1], 0, v1, s[0:1]
	s_waitcnt vmcnt(32)
	v_lshlrev_b32_e32 v2, 16, v95
	v_max_f32_e32 v2, v2, v2
	v_med3_f32 v2, v2, s85, v215
	v_mul_f32_e32 v2, 0xbfb8aa3b, v2
	v_exp_f32_e32 v2, v2
	s_waitcnt vmcnt(31)
	v_lshlrev_b32_e32 v42, 16, v96
	v_max_f32_e32 v42, v42, v42
	v_med3_f32 v42, v42, s85, v215
	v_mul_f32_e32 v3, v11, v45
	v_mul_f32_e32 v42, 0xbfb8aa3b, v42
	v_mul_f32_e32 v41, v3, v47
	v_add_f32_e32 v3, 1.0, v2
	v_exp_f32_e32 v47, v42
	v_mul_f32_e32 v42, v11, v49
	v_fma_f32 v40, v11, v51, v16
	v_rcp_f32_e32 v3, v3
	v_mul_f32_e32 v43, v42, v51
	s_waitcnt vmcnt(30)
	v_lshlrev_b32_e32 v44, 16, v97
	v_max_f32_e32 v44, v44, v44
	v_med3_f32 v44, v44, s85, v215
	v_mul_f32_e32 v44, 0xbfb8aa3b, v44
	v_exp_f32_e32 v51, v44
	v_add_f32_e32 v45, 1.0, v47
	v_mul_f32_e32 v2, v11, v2
	v_rcp_f32_e32 v49, v45
	v_mul_f32_e32 v45, v2, v3
	v_add_f32_e32 v2, 1.0, v51
	v_rcp_f32_e32 v53, v2
	s_waitcnt vmcnt(29)
	v_lshlrev_b32_e32 v2, 16, v98
	v_max_f32_e32 v2, v2, v2
	v_med3_f32 v2, v2, s85, v215
	v_mul_f32_e32 v2, 0xbfb8aa3b, v2
	v_exp_f32_e32 v54, v2
	s_mov_b32 s0, 0x2c000
	v_add_co_u32_e64 v2, s[0:1], s0, v0
	v_fma_f32 v42, v11, v3, v16
	s_nop 0
	v_addc_co_u32_e64 v3, s[0:1], 0, v1, s[0:1]
	v_mul_f32_e32 v2, v11, v47
	v_mul_f32_e32 v47, v2, v49
	v_add_f32_e32 v2, 1.0, v54
	v_rcp_f32_e32 v55, v2
	s_waitcnt vmcnt(28)
	v_lshlrev_b32_e32 v2, 16, v99
	v_max_f32_e32 v2, v2, v2
	v_med3_f32 v2, v2, s85, v215
	v_mul_f32_e32 v2, 0xbfb8aa3b, v2
	v_exp_f32_e32 v56, v2
	v_mul_f32_e32 v2, v11, v51
	v_fma_f32 v44, v11, v49, v16
	v_mul_f32_e32 v49, v2, v53
	v_add_f32_e32 v2, 1.0, v56
	s_mov_b32 s0, 0x2e000
	v_fma_f32 v46, v11, v53, v16
	v_rcp_f32_e32 v53, v2
	v_add_co_u32_e64 v2, s[0:1], s0, v0
	v_fma_f32 v48, v11, v55, v16
	s_nop 0
	v_addc_co_u32_e64 v3, s[0:1], 0, v1, s[0:1]
	s_mov_b32 s0, 0x30000
	v_add_co_u32_e64 v2, s[0:1], s0, v0
	s_nop 1
	v_addc_co_u32_e64 v3, s[0:1], 0, v1, s[0:1]
	s_waitcnt vmcnt(27)
	v_lshlrev_b32_e32 v2, 16, v100
	v_max_f32_e32 v2, v2, v2
	v_med3_f32 v2, v2, s85, v215
	v_mul_f32_e32 v2, 0xbfb8aa3b, v2
	v_exp_f32_e32 v59, v2
	v_mul_f32_e32 v2, v11, v54
	v_mul_f32_e32 v51, v2, v55
	s_mov_b32 s0, 0x32000
	v_add_f32_e32 v2, 1.0, v59
	v_rcp_f32_e32 v55, v2
	v_add_co_u32_e64 v2, s[0:1], s0, v0
	v_fma_f32 v50, v11, v53, v16
	s_nop 0
	v_addc_co_u32_e64 v3, s[0:1], 0, v1, s[0:1]
	s_mov_b32 s0, 0x34000
	v_add_co_u32_e64 v2, s[0:1], s0, v0
	s_nop 1
	v_addc_co_u32_e64 v3, s[0:1], 0, v1, s[0:1]
	s_waitcnt vmcnt(26)
	v_lshlrev_b32_e32 v2, 16, v101
	v_max_f32_e32 v2, v2, v2
	v_med3_f32 v2, v2, s85, v215
	v_mul_f32_e32 v2, 0xbfb8aa3b, v2
	v_exp_f32_e32 v52, v2
	v_mul_f32_e32 v2, v11, v56
	v_mul_f32_e32 v54, v2, v53
	s_mov_b32 s0, 0x36000
	v_add_f32_e32 v2, 1.0, v52
	v_rcp_f32_e32 v60, v2
	v_add_co_u32_e64 v2, s[0:1], s0, v0
	v_mul_f32_e32 v52, v11, v52
	s_nop 0
	v_addc_co_u32_e64 v3, s[0:1], 0, v1, s[0:1]
	s_mov_b32 s0, 0x38000
	v_add_co_u32_e64 v2, s[0:1], s0, v0
	v_fma_f32 v53, v11, v55, v16
	s_nop 0
	v_addc_co_u32_e64 v3, s[0:1], 0, v1, s[0:1]
	v_mul_f32_e32 v2, v11, v59
	v_mul_f32_e32 v56, v2, v55
	s_waitcnt vmcnt(25)
	v_lshlrev_b32_e32 v2, 16, v102
	v_max_f32_e32 v2, v2, v2
	v_med3_f32 v2, v2, s85, v215
	v_mul_f32_e32 v2, 0xbfb8aa3b, v2
	s_mov_b32 s0, 0x3a000
	v_exp_f32_e32 v59, v2
	v_add_co_u32_e64 v2, s[0:1], s0, v0
	v_fma_f32 v55, v11, v60, v16
	s_nop 0
	v_addc_co_u32_e64 v3, s[0:1], 0, v1, s[0:1]
	s_mov_b32 s0, 0x3c000
	s_nop 0
	v_add_co_u32_e64 v0, s[0:1], s0, v0
	s_nop 0
	v_addc_co_u32_e64 v1, s[0:1], 0, v1, s[0:1]
	s_waitcnt vmcnt(24)
	v_lshlrev_b32_e32 v3, 16, v103
	v_max_f32_e32 v1, v3, v3
	v_med3_f32 v1, v1, s85, v215
	v_add_f32_e32 v3, 1.0, v59
	v_mul_f32_e32 v1, 0xbfb8aa3b, v1
	v_rcp_f32_e32 v3, v3
	v_exp_f32_e32 v1, v1
	v_mul_f32_e32 v59, v11, v59
	v_mul_f32_e32 v58, v52, v60
	v_fma_f32 v57, v11, v3, v16
	v_mul_f32_e32 v60, v59, v3
	s_waitcnt vmcnt(23)
	v_lshlrev_b32_e32 v3, 16, v104
	v_add_f32_e32 v52, 1.0, v1
	v_max_f32_e32 v3, v3, v3
	s_waitcnt vmcnt(22)
	v_lshlrev_b32_e32 v61, 16, v105
	v_rcp_f32_e32 v52, v52
	v_med3_f32 v3, v3, s85, v215
	v_max_f32_e32 v61, v61, v61
	v_mul_f32_e32 v3, 0xbfb8aa3b, v3
	v_med3_f32 v61, v61, s85, v215
	v_exp_f32_e32 v3, v3
	v_mul_f32_e32 v61, 0xbfb8aa3b, v61
	v_mul_f32_e32 v1, v11, v1
	v_exp_f32_e32 v67, v61
	v_fma_f32 v59, v11, v52, v16
	v_mul_f32_e32 v62, v1, v52
	v_add_f32_e32 v61, 1.0, v3
	v_rcp_f32_e32 v63, v61
	v_add_f32_e32 v1, 1.0, v67
	v_rcp_f32_e32 v1, v1
	s_waitcnt vmcnt(21)
	v_lshlrev_b32_e32 v52, 16, v106
	v_max_f32_e32 v52, v52, v52
	v_med3_f32 v52, v52, s85, v215
	v_mul_f32_e32 v52, 0xbfb8aa3b, v52
	v_exp_f32_e32 v52, v52
	v_mul_f32_e32 v3, v11, v3
	s_waitcnt vmcnt(20)
	v_lshlrev_b32_e32 v65, 16, v107
	v_max_f32_e32 v65, v65, v65
	v_med3_f32 v65, v65, s85, v215
	v_mul_f32_e32 v64, v3, v63
	v_mul_f32_e32 v3, v11, v67
	v_mul_f32_e32 v65, 0xbfb8aa3b, v65
	v_exp_f32_e32 v71, v65
	v_add_f32_e32 v65, 1.0, v52
	v_mul_f32_e32 v66, v3, v1
	v_mul_f32_e32 v3, v11, v52
	v_fma_f32 v61, v11, v63, v16
	v_fma_f32 v63, v11, v1, v16
	v_rcp_f32_e32 v67, v65
	v_add_f32_e32 v1, 1.0, v71
	v_rcp_f32_e32 v1, v1
	v_cmp_gt_i32_e64 s[0:1], 3, v15
	v_mul_f32_e32 v68, v3, v67
	s_waitcnt vmcnt(19)
	v_lshlrev_b32_e32 v52, 16, v108
	v_max_f32_e32 v52, v52, v52
	v_med3_f32 v52, v52, s85, v215
	v_mul_f32_e32 v52, 0xbfb8aa3b, v52
	v_exp_f32_e32 v52, v52
	v_mul_f32_e32 v3, v11, v71
	s_waitcnt vmcnt(18)
	v_lshlrev_b32_e32 v69, 16, v109
	v_max_f32_e32 v69, v69, v69
	v_med3_f32 v69, v69, s85, v215
	v_mul_f32_e32 v69, 0xbfb8aa3b, v69
	v_exp_f32_e32 v73, v69
	v_add_f32_e32 v69, 1.0, v52
	v_fma_f32 v65, v11, v67, v16
	v_fma_f32 v67, v11, v1, v16
	v_rcp_f32_e32 v71, v69
	v_mul_f32_e32 v70, v3, v1
	v_add_f32_e32 v1, 1.0, v73
	v_rcp_f32_e32 v1, v1
	v_mul_f32_e32 v3, v11, v52
	v_mul_f32_e32 v72, v3, v71
	v_mul_f32_e32 v3, v11, v73
	v_fma_f32 v69, v11, v71, v16
	v_fma_f32 v71, v11, v1, v16
	v_mul_f32_e32 v74, v3, v1
	s_waitcnt vmcnt(17)
	v_lshlrev_b32_e32 v2, 16, v110
	v_max_f32_e32 v2, v2, v2
	s_waitcnt vmcnt(16)
	v_lshlrev_b32_e32 v0, 16, v111
	s_add_i32 s100, s12, s16
	s_cmpk_gt_i32 s100, 0x3ff
	s_cbranch_scc1 .Lhga_nopf
	s_bfe_u32 m0, s100, 0x20005
	s_lshr_b32 s101, s100, 7
	s_lshl_b32 s101, s101, 12
	s_and_b32 s100, s100, 31
	s_lshl_b32 s100, s100, 7
	s_or_b32 s101, s101, s100
	s_mul_i32 s101, s101, 0x1f00
	s_lshl_b32 s100, m0, 7
	s_add_u32 s101, s101, s100
	s_add_u32 s100, s22, s101
	s_addc_u32 s101, s23, 0
	v_readlane_b32 vcc_lo, v255, 33
	s_lshl_b32 m0, m0, 6
	s_nop 1
	s_or_b32 m0, m0, vcc_lo
	s_lshl_b32 m0, m0, 2
	v_readlane_b32 vcc_lo, v253, 10
	v_readlane_b32 vcc_hi, v253, 11
	s_nop 1
	s_add_u32 vcc_lo, vcc_lo, m0
	s_addc_u32 vcc_hi, vcc_hi, 0
	global_load_dwordx4 v[114:117], v123, s[100:101]
	global_load_dwordx4 v[118:121], v123, s[100:101] offset:16
	global_load_dword v122, v124, vcc
	global_load_ushort v80, v140, s[100:101] offset:-3968
	global_load_ushort v81, v140, s[100:101] offset:3968
	global_load_ushort v82, v141, s[100:101] offset:-3968
	global_load_ushort v83, v141, s[100:101] offset:3968
	global_load_ushort v84, v142, s[100:101] offset:-3968
	global_load_ushort v85, v142, s[100:101] offset:3968
	global_load_ushort v86, v143, s[100:101] offset:-3968
	global_load_ushort v87, v143, s[100:101] offset:3968
	global_load_ushort v88, v144, s[100:101] offset:-3968
	global_load_ushort v89, v144, s[100:101] offset:3968
	global_load_ushort v90, v145, s[100:101] offset:-3968
	global_load_ushort v91, v145, s[100:101] offset:3968
	global_load_ushort v92, v146, s[100:101] offset:-3968
	global_load_ushort v93, v146, s[100:101] offset:3968
	global_load_ushort v94, v147, s[100:101] offset:-3968
	global_load_ushort v95, v147, s[100:101] offset:3968
	global_load_ushort v96, v148, s[100:101] offset:-3968
	global_load_ushort v97, v148, s[100:101] offset:3968
	global_load_ushort v98, v149, s[100:101] offset:-3968
	global_load_ushort v99, v149, s[100:101] offset:3968
	global_load_ushort v100, v150, s[100:101] offset:-3968
	global_load_ushort v101, v150, s[100:101] offset:3968
	global_load_ushort v102, v151, s[100:101] offset:-3968
	global_load_ushort v103, v151, s[100:101] offset:3968
	global_load_ushort v104, v152, s[100:101] offset:-3968
	global_load_ushort v105, v152, s[100:101] offset:3968
	global_load_ushort v106, v153, s[100:101] offset:-3968
	global_load_ushort v107, v153, s[100:101] offset:3968
	global_load_ushort v108, v154, s[100:101] offset:-3968
	global_load_ushort v109, v154, s[100:101] offset:3968
	global_load_ushort v110, v155, s[100:101] offset:-3968
	global_load_ushort v111, v155, s[100:101] offset:3968
.Lhga_nopf:
	v_bfe_u32 v126, v200, 6, 1
	v_cmp_eq_u32_e32 vcc, 1, v126
	v_max_f32_e32 v0, v0, v0
	v_med3_f32 v0, v0, s85, v215
	v_mul_f32_e32 v0, 0xbfb8aa3b, v0
	v_exp_f32_e32 v0, v0
	v_med3_f32 v2, v2, s85, v215
	v_mul_f32_e32 v2, 0xbfb8aa3b, v2
	v_exp_f32_e32 v2, v2
	v_add_f32_e32 v1, 1.0, v0
	v_rcp_f32_e32 v1, v1
	v_mul_f32_e32 v0, v11, v0
	v_add_f32_e32 v52, 1.0, v2
	v_rcp_f32_e32 v52, v52
	v_mul_f32_e32 v78, v0, v1
	v_mul_f32_e32 v0, v31, v12
	v_mul_f32_e32 v0, v0, v13
	v_mul_f32_e32 v0, v0, v17
	v_mul_f32_e32 v0, v0, v19
	v_mul_f32_e32 v0, v0, v20
	v_mul_f32_e32 v0, v0, v23
	v_mul_f32_e32 v0, v0, v25
	v_mul_f32_e32 v0, v0, v27
	v_mul_f32_e32 v0, v0, v29
	v_mul_f32_e32 v0, v0, v32
	v_mul_f32_e32 v0, v0, v34
	v_mul_f32_e32 v0, v0, v36
	v_mul_f32_e32 v0, v0, v38
	v_mul_f32_e32 v0, v0, v40
	v_mul_f32_e32 v0, v0, v42
	v_mul_f32_e32 v0, v0, v44
	v_mul_f32_e32 v0, v0, v46
	v_mul_f32_e32 v0, v0, v48
	v_mul_f32_e32 v0, v0, v50
	v_mul_f32_e32 v0, v0, v53
	v_mul_f32_e32 v0, v0, v55
	v_mul_f32_e32 v0, v0, v57
	v_mul_f32_e32 v0, v0, v59
	v_mul_f32_e32 v0, v0, v61
	v_mul_f32_e32 v0, v0, v63
	v_mul_f32_e32 v0, v0, v65
	v_mul_f32_e32 v0, v0, v67
	v_mul_f32_e32 v0, v0, v69
	v_fma_f32 v73, v11, v52, v16
	v_mul_f32_e32 v0, v0, v71
	v_mul_f32_e32 v2, v11, v2
	v_fmac_f32_e32 v16, v11, v1
	v_mul_f32_e32 v0, v0, v73
	v_mul_f32_e32 v76, v2, v52
	v_mul_f32_e32 v52, v0, v16
	v_lshl_add_u32 v0, v5, 2, v75
	v_lshl_add_u32 v1, v15, 8, v0
	ds_write_b32 v1, v52 offset:55296
	s_waitcnt lgkmcnt(0)
	s_barrier
	ds_read2st64_b32 v[2:3], v0 offset0:216 offset1:217
	ds_read2st64_b32 v[0:1], v0 offset0:218 offset1:219
	v_mul_lo_u32 v75, v15, s2
	v_add3_u32 v22, v22, v75, v128
	s_and_saveexec_b64 s[2:3], vcc
	s_xor_b64 s[2:3], exec, s[2:3]
	s_cbranch_execz .LBB0_312
	v_cmp_lt_i32_e32 vcc, 0, v15
	s_waitcnt lgkmcnt(1)
	s_nop 0
	v_cndmask_b32_e32 v16, 1.0, v2, vcc
	v_mul_f32_e32 v75, v16, v3
	v_cmp_lt_i32_e32 vcc, 1, v15
	s_nop 1
	v_cndmask_b32_e32 v16, v16, v75, vcc
	s_waitcnt lgkmcnt(0)
	v_mul_f32_e32 v75, v0, v16
	v_cmp_lt_i32_e32 vcc, 2, v15
	s_nop 1
	v_cndmask_b32_e32 v16, v16, v75, vcc
	v_mul_f32_e32 v75, v1, v16
	v_cmp_lt_i32_e32 vcc, 3, v15
	s_nop 1
	v_cndmask_b32_e32 v75, v16, v75, vcc
	v_mul_f32_e32 v77, v31, v75
	v_mul_f32_e32 v12, v12, v77
	v_mul_f32_e32 v14, v14, v12
	v_mul_f32_e32 v12, v13, v12
	v_mul_f32_e32 v13, v18, v12
	v_cvt_pk_bf16_f32 v13, v13, s0
	v_mul_f32_e32 v12, v17, v12
	ds_write_b16 v22, v13 offset:432
	v_mul_f32_e32 v13, v21, v12
	v_cvt_pk_bf16_f32 v13, v13, s0
	v_mul_f32_e32 v12, v19, v12
	ds_write_b16 v22, v13 offset:576
	v_mul_f32_e32 v13, v24, v12
	v_cvt_pk_bf16_f32 v13, v13, s0
	v_mul_f32_e32 v12, v20, v12
	ds_write_b16 v22, v13 offset:720
	v_mul_f32_e32 v13, v26, v12
	v_cvt_pk_bf16_f32 v13, v13, s0
	v_mul_f32_e32 v12, v23, v12
	ds_write_b16 v22, v13 offset:864
	v_mul_f32_e32 v13, v28, v12
	v_cvt_pk_bf16_f32 v13, v13, s0
	v_mul_f32_e32 v12, v25, v12
	ds_write_b16 v22, v13 offset:1008
	v_mul_f32_e32 v13, v30, v12
	v_cvt_pk_bf16_f32 v13, v13, s0
	v_mul_f32_e32 v12, v27, v12
	ds_write_b16 v22, v13 offset:1152
	v_mul_f32_e32 v13, v33, v12
	v_cvt_pk_bf16_f32 v13, v13, s0
	v_mul_f32_e32 v12, v29, v12
	ds_write_b16 v22, v13 offset:1296
	v_mul_f32_e32 v13, v35, v12
	v_cvt_pk_bf16_f32 v13, v13, s0
	v_mul_f32_e32 v12, v32, v12
	ds_write_b16 v22, v13 offset:1440
	v_mul_f32_e32 v13, v37, v12
	v_cvt_pk_bf16_f32 v13, v13, s0
	v_mul_f32_e32 v12, v34, v12
	ds_write_b16 v22, v13 offset:1584
	v_mul_f32_e32 v13, v39, v12
	v_cvt_pk_bf16_f32 v13, v13, s0
	v_mul_f32_e32 v12, v36, v12
	ds_write_b16 v22, v13 offset:1728
	v_mul_f32_e32 v13, v41, v12
	v_cvt_pk_bf16_f32 v13, v13, s0
	v_mul_f32_e32 v12, v38, v12
	ds_write_b16 v22, v13 offset:1872
	v_mul_f32_e32 v13, v43, v12
	v_cvt_pk_bf16_f32 v13, v13, s0
	v_mul_f32_e32 v12, v40, v12
	ds_write_b16 v22, v13 offset:2016
	v_mul_f32_e32 v13, v45, v12
	v_cvt_pk_bf16_f32 v13, v13, s0
	v_mul_f32_e32 v12, v42, v12
	ds_write_b16 v22, v13 offset:2160
	v_mul_f32_e32 v13, v47, v12
	v_cvt_pk_bf16_f32 v13, v13, s0
	v_mul_f32_e32 v12, v44, v12
	ds_write_b16 v22, v13 offset:2304
	v_mul_f32_e32 v13, v49, v12
	v_cvt_pk_bf16_f32 v13, v13, s0
	v_mul_f32_e32 v12, v46, v12
	ds_write_b16 v22, v13 offset:2448
	v_mul_f32_e32 v13, v51, v12
	v_cvt_pk_bf16_f32 v13, v13, s0
	v_mul_f32_e32 v12, v48, v12
	ds_write_b16 v22, v13 offset:2592
	v_mul_f32_e32 v13, v54, v12
	v_cvt_pk_bf16_f32 v13, v13, s0
	v_mul_f32_e32 v12, v50, v12
	ds_write_b16 v22, v13 offset:2736
	v_mul_f32_e32 v13, v56, v12
	v_cvt_pk_bf16_f32 v13, v13, s0
	v_mul_f32_e32 v12, v53, v12
	ds_write_b16 v22, v13 offset:2880
	v_mul_f32_e32 v13, v58, v12
	v_cvt_pk_bf16_f32 v13, v13, s0
	v_mul_f32_e32 v12, v55, v12
	ds_write_b16 v22, v13 offset:3024
	v_mul_f32_e32 v13, v60, v12
	v_cvt_pk_bf16_f32 v13, v13, s0
	v_mul_f32_e32 v12, v57, v12
	ds_write_b16 v22, v13 offset:3168
	v_mul_f32_e32 v13, v62, v12
	v_cvt_pk_bf16_f32 v13, v13, s0
	v_mul_f32_e32 v12, v59, v12
	ds_write_b16 v22, v13 offset:3312
	v_mul_f32_e32 v13, v64, v12
	v_cvt_pk_bf16_f32 v13, v13, s0
	v_mul_f32_e32 v12, v61, v12
	ds_write_b16 v22, v13 offset:3456
	v_mul_f32_e32 v13, v66, v12
	v_cvt_pk_bf16_f32 v13, v13, s0
	v_mul_f32_e32 v12, v63, v12
	ds_write_b16 v22, v13 offset:3600
	v_mul_f32_e32 v13, v68, v12
	v_cvt_pk_bf16_f32 v13, v13, s0
	v_mul_f32_e32 v12, v65, v12
	ds_write_b16 v22, v13 offset:3744
	v_mul_f32_e32 v13, v70, v12
	v_cvt_pk_bf16_f32 v13, v13, s0
	v_mul_f32_e32 v12, v67, v12
	ds_write_b16 v22, v13 offset:3888
	v_mul_f32_e32 v13, v72, v12
	v_cvt_pk_bf16_f32 v13, v13, s0
	v_mul_f32_e32 v12, v69, v12
	ds_write_b16 v22, v13 offset:4032
	v_mul_f32_e32 v13, v74, v12
	v_cvt_pk_bf16_f32 v13, v13, s0
	v_mul_f32_e32 v12, v71, v12
	ds_write_b16 v22, v13 offset:4176
	v_mul_f32_e32 v13, v76, v12
	v_mul_f32_e32 v12, v73, v12
	v_mul_f32_e32 v12, v78, v12
	v_cvt_pk_bf16_f32 v14, v14, s0
	v_cvt_pk_bf16_f32 v13, v13, s0
	v_cvt_pk_bf16_f32 v12, v12, s0
	ds_write_b16 v22, v14 offset:288
	ds_write_b16 v22, v13 offset:4320
	ds_write_b16 v22, v12 offset:4464
